# EpiProj+EpiUpConv stores write-through (sc1), EpiProj redundant store-drain waits dropped
# speedup vs baseline: 1.0182x; 1.0182x over previous
.LBB0_149:
	s_waitcnt lgkmcnt(0)
	v_mov_b64_e32 v[160:161], s[52:53]
	v_mad_i64_i32 v[160:161], s[0:1], v206, s15, v[160:161]
	v_cvt_pk_bf16_f32 v162, v234, v235
	v_cvt_pk_bf16_f32 v163, v166, v167
	v_lshl_add_u64 v[160:161], v[204:205], 1, v[160:161]
	v_mov_b32_e32 v231, v230
	v_cvt_pk_bf16_f32 v164, v236, v237
	v_cvt_pk_bf16_f32 v165, v232, v233
	global_store_dwordx4 v[160:161], v[162:165], off sc1
	s_and_b64 vcc, exec, s[42:43]
	v_pk_mul_f32 v[166:167], v[144:145], v[230:231]
	v_mov_b32_e32 v162, v230
	v_mov_b32_e32 v163, v230
	v_pk_mul_f32 v[150:151], v[150:151], v[162:163]
	v_pk_mul_f32 v[164:165], v[148:149], v[230:231]
	v_pk_mul_f32 v[162:163], v[146:147], v[162:163]
	s_cbranch_vccnz .LBB0_157
	ds_swizzle_b32 v146, v164 offset:swizzle(SWAP,16)
	ds_swizzle_b32 v144, v166 offset:swizzle(SWAP,16)
	ds_swizzle_b32 v147, v165 offset:swizzle(SWAP,16)
	ds_swizzle_b32 v145, v167 offset:swizzle(SWAP,16)
	ds_swizzle_b32 v232, v150 offset:swizzle(SWAP,16)
	ds_swizzle_b32 v230, v162 offset:swizzle(SWAP,16)
	ds_swizzle_b32 v233, v151 offset:swizzle(SWAP,16)
	ds_swizzle_b32 v231, v163 offset:swizzle(SWAP,16)
	s_and_saveexec_b64 s[0:1], s[46:47]
	s_xor_b64 s[0:1], exec, s[0:1]
	s_cbranch_execz .LBB0_154
	s_and_saveexec_b64 s[4:5], s[44:45]
	s_cbranch_execz .LBB0_153
	s_waitcnt lgkmcnt(0)
	v_pk_mul_f32 v[146:147], v[172:173], v[146:147]
	v_pk_mul_f32 v[148:149], v[174:175], v[232:233]
	v_pk_fma_f32 v[164:165], v[164:165], v[168:169], v[146:147]
	v_pk_mul_f32 v[146:147], v[158:159], v[230:231]
	v_pk_mul_f32 v[144:145], v[156:157], v[144:145]
	v_pk_fma_f32 v[150:151], v[150:151], v[170:171], v[148:149]
	v_pk_fma_f32 v[162:163], v[162:163], v[154:155], v[146:147]
	v_pk_fma_f32 v[166:167], v[166:167], v[152:153], v[144:145]

.LBB0_159:
	s_waitcnt lgkmcnt(0)
	v_cvt_pk_bf16_f32 v144, v164, v165
	v_cvt_pk_bf16_f32 v145, v150, v151
	v_cvt_pk_bf16_f32 v146, v166, v167
	v_cvt_pk_bf16_f32 v147, v162, v163
	global_store_dwordx4 v[160:161], v[144:147], off offset:256 sc1
	v_pk_mul_f32 v[148:149], v[116:117], v[228:229] op_sel_hi:[1,0]
	s_and_b64 vcc, exec, s[42:43]
	v_pk_mul_f32 v[144:145], v[118:119], v[228:229] op_sel_hi:[1,0]
	v_pk_mul_f32 v[146:147], v[110:111], v[228:229] op_sel_hi:[1,0]
	v_pk_mul_f32 v[150:151], v[108:109], v[228:229] op_sel_hi:[1,0]
	s_cbranch_vccnz .LBB0_167
	ds_swizzle_b32 v116, v148 offset:swizzle(SWAP,16)
	ds_swizzle_b32 v108, v150 offset:swizzle(SWAP,16)
	ds_swizzle_b32 v117, v149 offset:swizzle(SWAP,16)
	ds_swizzle_b32 v109, v151 offset:swizzle(SWAP,16)
	ds_swizzle_b32 v162, v144 offset:swizzle(SWAP,16)
	ds_swizzle_b32 v160, v146 offset:swizzle(SWAP,16)
	ds_swizzle_b32 v163, v145 offset:swizzle(SWAP,16)
	ds_swizzle_b32 v161, v147 offset:swizzle(SWAP,16)
	s_and_saveexec_b64 s[0:1], s[46:47]
	s_xor_b64 s[0:1], exec, s[0:1]
	s_cbranch_execz .LBB0_164
	s_and_saveexec_b64 s[4:5], s[44:45]
	s_cbranch_execz .LBB0_163
	s_waitcnt lgkmcnt(0)
	v_pk_mul_f32 v[110:111], v[126:127], v[162:163]
	v_pk_mul_f32 v[116:117], v[124:125], v[116:117]
	v_pk_fma_f32 v[144:145], v[144:145], v[122:123], v[110:111]
	v_pk_mul_f32 v[110:111], v[114:115], v[160:161]
	v_pk_mul_f32 v[108:109], v[112:113], v[108:109]
	v_pk_fma_f32 v[148:149], v[148:149], v[120:121], v[116:117]
	v_pk_fma_f32 v[146:147], v[146:147], v[106:107], v[110:111]
	v_pk_fma_f32 v[150:151], v[150:151], v[104:105], v[108:109]

.LBB0_169:
	s_waitcnt lgkmcnt(0)
	v_mov_b64_e32 v[108:109], s[52:53]
	v_mad_i64_i32 v[108:109], s[0:1], v224, s15, v[108:109]
	v_mov_b32_e32 v229, v228
	v_cvt_pk_bf16_f32 v116, v148, v149
	v_cvt_pk_bf16_f32 v117, v144, v145
	v_cvt_pk_bf16_f32 v118, v150, v151
	v_cvt_pk_bf16_f32 v119, v146, v147
	v_lshl_add_u64 v[108:109], v[204:205], 1, v[108:109]
	v_mov_b32_e32 v110, v228
	v_mov_b32_e32 v111, v228
	global_store_dwordx4 v[108:109], v[116:119], off sc1
	v_pk_mul_f32 v[102:103], v[102:103], v[110:111]
	v_pk_mul_f32 v[110:111], v[98:99], v[110:111]
	v_pk_mul_f32 v[116:117], v[100:101], v[228:229]
	s_and_b64 vcc, exec, s[42:43]
	v_pk_mul_f32 v[118:119], v[96:97], v[228:229]
	s_cbranch_vccnz .LBB0_177
	ds_swizzle_b32 v98, v116 offset:swizzle(SWAP,16)
	ds_swizzle_b32 v96, v118 offset:swizzle(SWAP,16)
	ds_swizzle_b32 v99, v117 offset:swizzle(SWAP,16)
	ds_swizzle_b32 v97, v119 offset:swizzle(SWAP,16)
	ds_swizzle_b32 v146, v102 offset:swizzle(SWAP,16)
	ds_swizzle_b32 v144, v110 offset:swizzle(SWAP,16)
	ds_swizzle_b32 v147, v103 offset:swizzle(SWAP,16)
	ds_swizzle_b32 v145, v111 offset:swizzle(SWAP,16)
	s_and_saveexec_b64 s[0:1], s[46:47]
	s_xor_b64 s[0:1], exec, s[0:1]
	s_cbranch_execz .LBB0_174
	s_and_saveexec_b64 s[4:5], s[44:45]
	s_cbranch_execz .LBB0_173
	s_waitcnt lgkmcnt(0)
	v_pk_mul_f32 v[98:99], v[124:125], v[98:99]
	v_pk_mul_f32 v[100:101], v[126:127], v[146:147]
	v_pk_fma_f32 v[116:117], v[116:117], v[120:121], v[98:99]
	v_pk_mul_f32 v[98:99], v[114:115], v[144:145]
	v_pk_mul_f32 v[96:97], v[112:113], v[96:97]
	v_pk_fma_f32 v[102:103], v[102:103], v[122:123], v[100:101]
	v_pk_fma_f32 v[110:111], v[110:111], v[106:107], v[98:99]
	v_pk_fma_f32 v[118:119], v[118:119], v[104:105], v[96:97]

.LBB0_179:
	s_waitcnt lgkmcnt(0)
	v_cvt_pk_bf16_f32 v96, v116, v117
	v_cvt_pk_bf16_f32 v97, v102, v103
	v_cvt_pk_bf16_f32 v98, v118, v119
	v_cvt_pk_bf16_f32 v99, v110, v111
	s_and_b64 vcc, exec, s[42:43]
	global_store_dwordx4 v[108:109], v[96:99], off offset:256 sc1
	s_cbranch_vccnz .LBB0_181
	s_nop 0
	v_lshlrev_b64 v[96:97], 6, v[220:221]
	v_lshl_add_u64 v[96:97], s[56:57], 0, v[96:97]
	global_load_dwordx4 v[148:151], v[96:97], off offset:48
	global_load_dwordx4 v[164:167], v[96:97], off offset:32
	global_load_dwordx4 v[144:147], v[96:97], off offset:16
	global_load_dwordx4 v[160:163], v[96:97], off
	v_lshlrev_b64 v[96:97], 6, v[216:217]
	v_lshl_add_u64 v[108:109], s[56:57], 0, v[96:97]
	global_load_dwordx4 v[100:103], v[108:109], off offset:48
	global_load_dwordx4 v[116:119], v[108:109], off offset:32
	global_load_dwordx4 v[96:99], v[108:109], off offset:16
	s_nop 0
	global_load_dwordx4 v[108:111], v[108:109], off

.LBB0_191:
	s_waitcnt lgkmcnt(0)
	v_mov_b64_e32 v[136:137], s[52:53]
	v_mad_i64_i32 v[136:137], s[0:1], v220, s15, v[136:137]
	v_cvt_pk_bf16_f32 v138, v228, v229
	v_cvt_pk_bf16_f32 v139, v142, v143
	v_lshl_add_u64 v[136:137], v[204:205], 1, v[136:137]
	v_mov_b32_e32 v227, v226
	v_cvt_pk_bf16_f32 v140, v230, v231
	v_cvt_pk_bf16_f32 v141, v224, v225
	global_store_dwordx4 v[136:137], v[138:141], off sc1
	s_and_b64 vcc, exec, s[42:43]
	v_pk_mul_f32 v[142:143], v[128:129], v[226:227]
	v_mov_b32_e32 v138, v226
	v_mov_b32_e32 v139, v226
	v_pk_mul_f32 v[134:135], v[134:135], v[138:139]
	v_pk_mul_f32 v[140:141], v[132:133], v[226:227]
	v_pk_mul_f32 v[138:139], v[130:131], v[138:139]
	s_cbranch_vccnz .LBB0_199
	ds_swizzle_b32 v130, v140 offset:swizzle(SWAP,16)
	ds_swizzle_b32 v128, v142 offset:swizzle(SWAP,16)
	ds_swizzle_b32 v131, v141 offset:swizzle(SWAP,16)
	ds_swizzle_b32 v129, v143 offset:swizzle(SWAP,16)
	ds_swizzle_b32 v224, v134 offset:swizzle(SWAP,16)
	ds_swizzle_b32 v220, v138 offset:swizzle(SWAP,16)
	ds_swizzle_b32 v225, v135 offset:swizzle(SWAP,16)
	ds_swizzle_b32 v221, v139 offset:swizzle(SWAP,16)
	s_and_saveexec_b64 s[0:1], s[46:47]
	s_xor_b64 s[0:1], exec, s[0:1]
	s_cbranch_execz .LBB0_196
	s_and_saveexec_b64 s[4:5], s[44:45]
	s_cbranch_execz .LBB0_195
	s_waitcnt lgkmcnt(0)
	v_pk_mul_f32 v[130:131], v[164:165], v[130:131]
	v_pk_mul_f32 v[132:133], v[166:167], v[224:225]
	v_pk_fma_f32 v[140:141], v[140:141], v[160:161], v[130:131]
	v_pk_mul_f32 v[130:131], v[150:151], v[220:221]
	v_pk_mul_f32 v[128:129], v[148:149], v[128:129]
	v_pk_fma_f32 v[134:135], v[134:135], v[162:163], v[132:133]
	v_pk_fma_f32 v[138:139], v[138:139], v[146:147], v[130:131]
	v_pk_fma_f32 v[142:143], v[142:143], v[144:145], v[128:129]

.LBB0_201:
	s_waitcnt lgkmcnt(0)
	v_cvt_pk_bf16_f32 v128, v140, v141
	v_cvt_pk_bf16_f32 v129, v134, v135
	v_cvt_pk_bf16_f32 v130, v142, v143
	v_cvt_pk_bf16_f32 v131, v138, v139
	global_store_dwordx4 v[136:137], v[128:131], off offset:256 sc1
	v_pk_mul_f32 v[94:95], v[94:95], v[222:223] op_sel_hi:[1,0]
	s_and_b64 vcc, exec, s[42:43]
	v_pk_mul_f32 v[130:131], v[92:93], v[222:223] op_sel_hi:[1,0]
	v_pk_mul_f32 v[128:129], v[90:91], v[222:223] op_sel_hi:[1,0]
	v_pk_mul_f32 v[132:133], v[88:89], v[222:223] op_sel_hi:[1,0]
	s_cbranch_vccnz .LBB0_209
	ds_swizzle_b32 v90, v130 offset:swizzle(SWAP,16)
	ds_swizzle_b32 v88, v132 offset:swizzle(SWAP,16)
	ds_swizzle_b32 v91, v131 offset:swizzle(SWAP,16)
	ds_swizzle_b32 v89, v133 offset:swizzle(SWAP,16)
	ds_swizzle_b32 v136, v94 offset:swizzle(SWAP,16)
	ds_swizzle_b32 v134, v128 offset:swizzle(SWAP,16)
	ds_swizzle_b32 v137, v95 offset:swizzle(SWAP,16)
	ds_swizzle_b32 v135, v129 offset:swizzle(SWAP,16)
	s_and_saveexec_b64 s[0:1], s[46:47]
	s_xor_b64 s[0:1], exec, s[0:1]
	s_cbranch_execz .LBB0_206
	s_and_saveexec_b64 s[4:5], s[44:45]
	s_cbranch_execz .LBB0_205
	s_waitcnt lgkmcnt(0)
	v_pk_mul_f32 v[90:91], v[116:117], v[90:91]
	v_pk_mul_f32 v[92:93], v[118:119], v[136:137]
	v_pk_fma_f32 v[130:131], v[130:131], v[108:109], v[90:91]
	v_pk_mul_f32 v[90:91], v[102:103], v[134:135]
	v_pk_mul_f32 v[88:89], v[100:101], v[88:89]
	v_pk_fma_f32 v[94:95], v[94:95], v[110:111], v[92:93]
	v_pk_fma_f32 v[128:129], v[128:129], v[98:99], v[90:91]
	v_pk_fma_f32 v[132:133], v[132:133], v[96:97], v[88:89]

.LBB0_211:
	s_waitcnt lgkmcnt(0)
	v_mov_b64_e32 v[88:89], s[52:53]
	v_mad_i64_i32 v[88:89], s[0:1], v216, s15, v[88:89]
	v_cvt_pk_bf16_f32 v90, v130, v131
	v_cvt_pk_bf16_f32 v91, v94, v95
	v_lshl_add_u64 v[88:89], v[204:205], 1, v[88:89]
	v_mov_b32_e32 v223, v222
	v_cvt_pk_bf16_f32 v92, v132, v133
	v_cvt_pk_bf16_f32 v93, v128, v129
	global_store_dwordx4 v[88:89], v[90:93], off sc1
	s_and_b64 vcc, exec, s[42:43]
	v_pk_mul_f32 v[94:95], v[80:81], v[222:223]
	v_mov_b32_e32 v90, v222
	v_mov_b32_e32 v91, v222
	v_pk_mul_f32 v[86:87], v[86:87], v[90:91]
	v_pk_mul_f32 v[92:93], v[84:85], v[222:223]
	v_pk_mul_f32 v[90:91], v[82:83], v[90:91]
	s_cbranch_vccnz .LBB0_219
	ds_swizzle_b32 v82, v92 offset:swizzle(SWAP,16)
	ds_swizzle_b32 v80, v94 offset:swizzle(SWAP,16)
	ds_swizzle_b32 v83, v93 offset:swizzle(SWAP,16)
	ds_swizzle_b32 v81, v95 offset:swizzle(SWAP,16)
	ds_swizzle_b32 v130, v86 offset:swizzle(SWAP,16)
	ds_swizzle_b32 v128, v90 offset:swizzle(SWAP,16)
	ds_swizzle_b32 v131, v87 offset:swizzle(SWAP,16)
	ds_swizzle_b32 v129, v91 offset:swizzle(SWAP,16)
	s_and_saveexec_b64 s[0:1], s[46:47]
	s_xor_b64 s[0:1], exec, s[0:1]
	s_cbranch_execz .LBB0_216
	s_and_saveexec_b64 s[4:5], s[44:45]
	s_cbranch_execz .LBB0_215
	s_waitcnt lgkmcnt(0)
	v_pk_mul_f32 v[82:83], v[116:117], v[82:83]
	v_pk_mul_f32 v[84:85], v[118:119], v[130:131]
	v_pk_fma_f32 v[92:93], v[92:93], v[108:109], v[82:83]
	v_pk_mul_f32 v[82:83], v[102:103], v[128:129]
	v_pk_mul_f32 v[80:81], v[100:101], v[80:81]
	v_pk_fma_f32 v[86:87], v[86:87], v[110:111], v[84:85]
	v_pk_fma_f32 v[90:91], v[90:91], v[98:99], v[82:83]
	v_pk_fma_f32 v[94:95], v[94:95], v[96:97], v[80:81]

.LBB0_221:
	s_waitcnt lgkmcnt(0)
	v_cvt_pk_bf16_f32 v80, v92, v93
	v_cvt_pk_bf16_f32 v81, v86, v87
	v_cvt_pk_bf16_f32 v82, v94, v95
	v_cvt_pk_bf16_f32 v83, v90, v91
	global_store_dwordx4 v[88:89], v[80:83], off offset:256 sc1
	s_and_b64 vcc, exec, s[42:43]
	s_nop 0
	v_add_u32_e32 v80, 0x80, v206
	v_ashrrev_i32_e32 v81, 31, v80
	s_cbranch_vccnz .LBB0_223
	v_lshlrev_b64 v[82:83], 6, v[80:81]
	v_lshl_add_u64 v[82:83], s[56:57], 0, v[82:83]
	global_load_dwordx4 v[156:159], v[82:83], off offset:48
	global_load_dwordx4 v[172:175], v[82:83], off offset:32
	global_load_dwordx4 v[152:155], v[82:83], off offset:16
	global_load_dwordx4 v[168:171], v[82:83], off
	v_lshlrev_b64 v[82:83], 6, v[206:207]
	v_lshl_add_u64 v[82:83], s[56:57], 0, v[82:83]
	s_mov_b64 s[0:1], 0x2400
	v_lshl_add_u64 v[84:85], v[82:83], 0, s[0:1]
	v_add_co_u32_e32 v82, vcc, s11, v82
	s_nop 1
	v_addc_co_u32_e32 v83, vcc, 0, v83, vcc
	global_load_dwordx4 v[120:123], v[82:83], off offset:1024
	global_load_dwordx4 v[112:115], v[84:85], off offset:48
	global_load_dwordx4 v[124:127], v[84:85], off offset:32
	global_load_dwordx4 v[104:107], v[84:85], off offset:16

.LBB0_233:
	s_waitcnt lgkmcnt(0)
	v_mov_b64_e32 v[72:73], s[52:53]
	v_mad_i64_i32 v[72:73], s[0:1], v80, s15, v[72:73]
	v_cvt_pk_bf16_f32 v74, v84, v85
	v_cvt_pk_bf16_f32 v75, v78, v79
	v_lshl_add_u64 v[72:73], v[204:205], 1, v[72:73]
	v_mov_b32_e32 v219, v218
	v_cvt_pk_bf16_f32 v76, v86, v87
	v_cvt_pk_bf16_f32 v77, v82, v83
	global_store_dwordx4 v[72:73], v[74:77], off sc1
	s_and_b64 vcc, exec, s[42:43]
	v_pk_mul_f32 v[78:79], v[64:65], v[218:219]
	v_mov_b32_e32 v74, v218
	v_mov_b32_e32 v75, v218
	v_pk_mul_f32 v[70:71], v[70:71], v[74:75]
	v_pk_mul_f32 v[76:77], v[68:69], v[218:219]
	v_pk_mul_f32 v[74:75], v[66:67], v[74:75]
	s_cbranch_vccnz .LBB0_241
	ds_swizzle_b32 v66, v76 offset:swizzle(SWAP,16)
	ds_swizzle_b32 v64, v78 offset:swizzle(SWAP,16)
	ds_swizzle_b32 v67, v77 offset:swizzle(SWAP,16)
	ds_swizzle_b32 v65, v79 offset:swizzle(SWAP,16)
	ds_swizzle_b32 v82, v70 offset:swizzle(SWAP,16)
	ds_swizzle_b32 v80, v74 offset:swizzle(SWAP,16)
	ds_swizzle_b32 v83, v71 offset:swizzle(SWAP,16)
	ds_swizzle_b32 v81, v75 offset:swizzle(SWAP,16)
	s_and_saveexec_b64 s[0:1], s[46:47]
	s_xor_b64 s[0:1], exec, s[0:1]
	s_cbranch_execz .LBB0_238
	s_and_saveexec_b64 s[4:5], s[44:45]
	s_cbranch_execz .LBB0_237
	s_waitcnt lgkmcnt(0)
	v_pk_mul_f32 v[66:67], v[172:173], v[66:67]
	v_pk_mul_f32 v[68:69], v[174:175], v[82:83]
	v_pk_fma_f32 v[76:77], v[76:77], v[168:169], v[66:67]
	v_pk_mul_f32 v[66:67], v[158:159], v[80:81]
	v_pk_mul_f32 v[64:65], v[156:157], v[64:65]
	v_pk_fma_f32 v[70:71], v[70:71], v[170:171], v[68:69]
	v_pk_fma_f32 v[74:75], v[74:75], v[154:155], v[66:67]
	v_pk_fma_f32 v[78:79], v[78:79], v[152:153], v[64:65]

.LBB0_243:
	s_waitcnt lgkmcnt(0)
	v_cvt_pk_bf16_f32 v64, v76, v77
	v_cvt_pk_bf16_f32 v65, v70, v71
	v_cvt_pk_bf16_f32 v66, v78, v79
	v_cvt_pk_bf16_f32 v67, v74, v75
	global_store_dwordx4 v[72:73], v[64:67], off offset:256 sc1
	v_pk_mul_f32 v[54:55], v[54:55], v[214:215] op_sel_hi:[1,0]
	s_and_b64 vcc, exec, s[42:43]
	v_pk_mul_f32 v[66:67], v[52:53], v[214:215] op_sel_hi:[1,0]
	v_pk_mul_f32 v[64:65], v[50:51], v[214:215] op_sel_hi:[1,0]
	v_pk_mul_f32 v[68:69], v[48:49], v[214:215] op_sel_hi:[1,0]
	s_cbranch_vccnz .LBB0_251
	ds_swizzle_b32 v50, v66 offset:swizzle(SWAP,16)
	ds_swizzle_b32 v48, v68 offset:swizzle(SWAP,16)
	ds_swizzle_b32 v51, v67 offset:swizzle(SWAP,16)
	ds_swizzle_b32 v49, v69 offset:swizzle(SWAP,16)
	ds_swizzle_b32 v72, v54 offset:swizzle(SWAP,16)
	ds_swizzle_b32 v70, v64 offset:swizzle(SWAP,16)
	ds_swizzle_b32 v73, v55 offset:swizzle(SWAP,16)
	ds_swizzle_b32 v71, v65 offset:swizzle(SWAP,16)
	s_and_saveexec_b64 s[0:1], s[46:47]
	s_xor_b64 s[0:1], exec, s[0:1]
	s_cbranch_execz .LBB0_248
	s_and_saveexec_b64 s[4:5], s[44:45]
	s_cbranch_execz .LBB0_247
	s_waitcnt lgkmcnt(0)
	v_pk_mul_f32 v[50:51], v[124:125], v[50:51]
	v_pk_mul_f32 v[52:53], v[126:127], v[72:73]
	v_pk_fma_f32 v[66:67], v[66:67], v[120:121], v[50:51]
	v_pk_mul_f32 v[50:51], v[114:115], v[70:71]
	v_pk_mul_f32 v[48:49], v[112:113], v[48:49]
	v_pk_fma_f32 v[54:55], v[54:55], v[122:123], v[52:53]
	v_pk_fma_f32 v[64:65], v[64:65], v[106:107], v[50:51]
	v_pk_fma_f32 v[68:69], v[68:69], v[104:105], v[48:49]

.LBB0_253:
	s_waitcnt lgkmcnt(0)
	v_mov_b64_e32 v[48:49], s[52:53]
	v_mad_i64_i32 v[48:49], s[0:1], v210, s15, v[48:49]
	v_cvt_pk_bf16_f32 v50, v66, v67
	v_cvt_pk_bf16_f32 v51, v54, v55
	v_lshl_add_u64 v[48:49], v[204:205], 1, v[48:49]
	v_mov_b32_e32 v215, v214
	v_cvt_pk_bf16_f32 v52, v68, v69
	v_cvt_pk_bf16_f32 v53, v64, v65
	global_store_dwordx4 v[48:49], v[50:53], off sc1
	s_and_b64 vcc, exec, s[42:43]
	v_pk_mul_f32 v[54:55], v[32:33], v[214:215]
	v_mov_b32_e32 v50, v214
	v_mov_b32_e32 v51, v214
	v_pk_mul_f32 v[38:39], v[38:39], v[50:51]
	v_pk_mul_f32 v[52:53], v[36:37], v[214:215]
	v_pk_mul_f32 v[50:51], v[34:35], v[50:51]
	s_cbranch_vccnz .LBB0_261
	ds_swizzle_b32 v34, v52 offset:swizzle(SWAP,16)
	ds_swizzle_b32 v32, v54 offset:swizzle(SWAP,16)
	ds_swizzle_b32 v35, v53 offset:swizzle(SWAP,16)
	ds_swizzle_b32 v33, v55 offset:swizzle(SWAP,16)
	ds_swizzle_b32 v66, v38 offset:swizzle(SWAP,16)
	ds_swizzle_b32 v64, v50 offset:swizzle(SWAP,16)
	ds_swizzle_b32 v67, v39 offset:swizzle(SWAP,16)
	ds_swizzle_b32 v65, v51 offset:swizzle(SWAP,16)
	s_and_saveexec_b64 s[0:1], s[46:47]
	s_xor_b64 s[0:1], exec, s[0:1]
	s_cbranch_execz .LBB0_258
	s_and_saveexec_b64 s[4:5], s[44:45]
	s_cbranch_execz .LBB0_257
	s_waitcnt lgkmcnt(0)
	v_pk_mul_f32 v[34:35], v[124:125], v[34:35]
	v_pk_mul_f32 v[36:37], v[126:127], v[66:67]
	v_pk_fma_f32 v[52:53], v[52:53], v[120:121], v[34:35]
	v_pk_mul_f32 v[34:35], v[114:115], v[64:65]
	v_pk_mul_f32 v[32:33], v[112:113], v[32:33]
	v_pk_fma_f32 v[38:39], v[38:39], v[122:123], v[36:37]
	v_pk_fma_f32 v[50:51], v[50:51], v[106:107], v[34:35]
	v_pk_fma_f32 v[54:55], v[54:55], v[104:105], v[32:33]

.LBB0_263:
	s_and_b64 vcc, exec, s[42:43]
	s_waitcnt lgkmcnt(0)
	v_cvt_pk_bf16_f32 v32, v52, v53
	v_cvt_pk_bf16_f32 v33, v38, v39
	v_cvt_pk_bf16_f32 v34, v54, v55
	v_cvt_pk_bf16_f32 v35, v50, v51
	global_store_dwordx4 v[48:49], v[32:35], off offset:256 sc1
	s_cbranch_vccnz .LBB0_265
	s_nop 0
	v_lshlrev_b64 v[32:33], 6, v[202:203]
	v_lshl_add_u64 v[32:33], s[56:57], 0, v[32:33]
	global_load_dwordx4 v[148:151], v[32:33], off offset:48
	global_load_dwordx4 v[164:167], v[32:33], off offset:32
	global_load_dwordx4 v[144:147], v[32:33], off offset:16
	global_load_dwordx4 v[160:163], v[32:33], off
	v_lshlrev_b64 v[32:33], 6, v[206:207]
	v_lshl_add_u64 v[32:33], s[56:57], 0, v[32:33]
	v_lshl_add_u64 v[34:35], v[32:33], 0, s[76:77]
	v_add_co_u32_e32 v32, vcc, s11, v32
	s_nop 1
	v_addc_co_u32_e32 v33, vcc, 0, v33, vcc
	global_load_dwordx4 v[108:111], v[32:33], off offset:3072
	global_load_dwordx4 v[100:103], v[34:35], off offset:48
	global_load_dwordx4 v[116:119], v[34:35], off offset:32
	global_load_dwordx4 v[96:99], v[34:35], off offset:16

.LBB0_275:
	s_waitcnt lgkmcnt(0)
	v_mov_b64_e32 v[24:25], s[52:53]
	v_mad_i64_i32 v[24:25], s[0:1], v202, s15, v[24:25]
	v_cvt_pk_bf16_f32 v26, v34, v35
	v_cvt_pk_bf16_f32 v27, v30, v31
	v_lshl_add_u64 v[24:25], v[204:205], 1, v[24:25]
	v_mov_b32_e32 v213, v212
	v_cvt_pk_bf16_f32 v28, v36, v37
	v_cvt_pk_bf16_f32 v29, v32, v33
	global_store_dwordx4 v[24:25], v[26:29], off sc1
	s_and_b64 vcc, exec, s[42:43]
	v_pk_mul_f32 v[30:31], v[16:17], v[212:213]
	v_mov_b32_e32 v26, v212
	v_mov_b32_e32 v27, v212
	v_pk_mul_f32 v[22:23], v[22:23], v[26:27]
	v_pk_mul_f32 v[28:29], v[20:21], v[212:213]
	v_pk_mul_f32 v[26:27], v[18:19], v[26:27]
	s_cbranch_vccnz .LBB0_283
	ds_swizzle_b32 v18, v28 offset:swizzle(SWAP,16)
	ds_swizzle_b32 v16, v30 offset:swizzle(SWAP,16)
	ds_swizzle_b32 v19, v29 offset:swizzle(SWAP,16)
	ds_swizzle_b32 v17, v31 offset:swizzle(SWAP,16)
	ds_swizzle_b32 v34, v22 offset:swizzle(SWAP,16)
	ds_swizzle_b32 v32, v26 offset:swizzle(SWAP,16)
	ds_swizzle_b32 v35, v23 offset:swizzle(SWAP,16)
	ds_swizzle_b32 v33, v27 offset:swizzle(SWAP,16)
	s_and_saveexec_b64 s[0:1], s[46:47]
	s_xor_b64 s[0:1], exec, s[0:1]
	s_cbranch_execz .LBB0_280
	s_and_saveexec_b64 s[4:5], s[44:45]
	s_cbranch_execz .LBB0_279
	s_waitcnt lgkmcnt(0)
	v_pk_mul_f32 v[18:19], v[164:165], v[18:19]
	v_pk_mul_f32 v[20:21], v[166:167], v[34:35]
	v_pk_fma_f32 v[28:29], v[28:29], v[160:161], v[18:19]
	v_pk_mul_f32 v[18:19], v[150:151], v[32:33]
	v_pk_mul_f32 v[16:17], v[148:149], v[16:17]
	v_pk_fma_f32 v[22:23], v[22:23], v[162:163], v[20:21]
	v_pk_fma_f32 v[26:27], v[26:27], v[146:147], v[18:19]
	v_pk_fma_f32 v[30:31], v[30:31], v[144:145], v[16:17]

.LBB0_285:
	s_waitcnt lgkmcnt(0)
	v_cvt_pk_bf16_f32 v16, v28, v29
	v_cvt_pk_bf16_f32 v17, v22, v23
	v_cvt_pk_bf16_f32 v18, v30, v31
	v_cvt_pk_bf16_f32 v19, v26, v27
	global_store_dwordx4 v[24:25], v[16:19], off offset:256 sc1
	v_pk_mul_f32 v[14:15], v[14:15], v[208:209] op_sel_hi:[1,0]
	s_and_b64 vcc, exec, s[42:43]
	v_pk_mul_f32 v[18:19], v[12:13], v[208:209] op_sel_hi:[1,0]
	v_pk_mul_f32 v[16:17], v[10:11], v[208:209] op_sel_hi:[1,0]
	v_pk_mul_f32 v[20:21], v[8:9], v[208:209] op_sel_hi:[1,0]
	s_cbranch_vccnz .LBB0_293
	ds_swizzle_b32 v10, v18 offset:swizzle(SWAP,16)
	ds_swizzle_b32 v8, v20 offset:swizzle(SWAP,16)
	ds_swizzle_b32 v11, v19 offset:swizzle(SWAP,16)
	ds_swizzle_b32 v9, v21 offset:swizzle(SWAP,16)
	ds_swizzle_b32 v24, v14 offset:swizzle(SWAP,16)
	ds_swizzle_b32 v22, v16 offset:swizzle(SWAP,16)
	ds_swizzle_b32 v25, v15 offset:swizzle(SWAP,16)
	ds_swizzle_b32 v23, v17 offset:swizzle(SWAP,16)
	s_and_saveexec_b64 s[0:1], s[46:47]
	s_xor_b64 s[0:1], exec, s[0:1]
	s_cbranch_execz .LBB0_290
	s_and_saveexec_b64 s[4:5], s[44:45]
	s_cbranch_execz .LBB0_289
	s_waitcnt lgkmcnt(0)
	v_pk_mul_f32 v[10:11], v[116:117], v[10:11]
	v_pk_mul_f32 v[12:13], v[118:119], v[24:25]
	v_pk_fma_f32 v[18:19], v[18:19], v[108:109], v[10:11]
	v_pk_mul_f32 v[10:11], v[102:103], v[22:23]
	v_pk_mul_f32 v[8:9], v[100:101], v[8:9]
	v_pk_fma_f32 v[14:15], v[14:15], v[110:111], v[12:13]
	v_pk_fma_f32 v[16:17], v[16:17], v[98:99], v[10:11]
	v_pk_fma_f32 v[20:21], v[20:21], v[96:97], v[8:9]

.LBB0_295:
	s_waitcnt lgkmcnt(0)
	v_mov_b64_e32 v[8:9], s[52:53]
	v_mad_i64_i32 v[8:9], s[0:1], v200, s15, v[8:9]
	v_cvt_pk_bf16_f32 v10, v18, v19
	v_cvt_pk_bf16_f32 v11, v14, v15
	v_lshl_add_u64 v[8:9], v[204:205], 1, v[8:9]
	v_mov_b32_e32 v209, v208
	v_cvt_pk_bf16_f32 v12, v20, v21
	v_cvt_pk_bf16_f32 v13, v16, v17
	global_store_dwordx4 v[8:9], v[10:13], off sc1
	s_and_b64 vcc, exec, s[42:43]
	v_pk_mul_f32 v[14:15], v[0:1], v[208:209]
	v_mov_b32_e32 v10, v208
	v_mov_b32_e32 v11, v208
	v_pk_mul_f32 v[6:7], v[6:7], v[10:11]
	v_pk_mul_f32 v[12:13], v[4:5], v[208:209]
	v_pk_mul_f32 v[10:11], v[2:3], v[10:11]
	s_cbranch_vccnz .LBB0_303
	ds_swizzle_b32 v2, v12 offset:swizzle(SWAP,16)
	ds_swizzle_b32 v0, v14 offset:swizzle(SWAP,16)
	ds_swizzle_b32 v3, v13 offset:swizzle(SWAP,16)
	ds_swizzle_b32 v1, v15 offset:swizzle(SWAP,16)
	ds_swizzle_b32 v18, v6 offset:swizzle(SWAP,16)
	ds_swizzle_b32 v16, v10 offset:swizzle(SWAP,16)
	ds_swizzle_b32 v19, v7 offset:swizzle(SWAP,16)
	ds_swizzle_b32 v17, v11 offset:swizzle(SWAP,16)
	s_and_saveexec_b64 s[0:1], s[46:47]
	s_xor_b64 s[0:1], exec, s[0:1]
	s_cbranch_execz .LBB0_300
	s_and_saveexec_b64 s[4:5], s[44:45]
	s_cbranch_execz .LBB0_299
	s_waitcnt lgkmcnt(0)
	v_pk_mul_f32 v[2:3], v[116:117], v[2:3]
	v_pk_mul_f32 v[4:5], v[118:119], v[18:19]
	v_pk_fma_f32 v[12:13], v[12:13], v[108:109], v[2:3]
	v_pk_mul_f32 v[2:3], v[102:103], v[16:17]
	v_pk_mul_f32 v[0:1], v[100:101], v[0:1]
	v_pk_fma_f32 v[6:7], v[6:7], v[110:111], v[4:5]
	v_pk_fma_f32 v[10:11], v[10:11], v[98:99], v[2:3]
	v_pk_fma_f32 v[14:15], v[14:15], v[96:97], v[0:1]

.LBB0_305:
	s_andn2_b64 vcc, exec, s[38:39]
	s_mov_b64 s[0:1], -1
	s_waitcnt lgkmcnt(0)
	v_cvt_pk_bf16_f32 v0, v12, v13
	v_cvt_pk_bf16_f32 v1, v6, v7
	v_cvt_pk_bf16_f32 v2, v14, v15
	v_cvt_pk_bf16_f32 v3, v10, v11
	global_store_dwordx4 v[8:9], v[0:3], off offset:256 sc1
	s_cbranch_vccnz .LBB0_104
	s_andn2_b64 vcc, exec, s[48:49]
	s_cbranch_vccnz .LBB0_103
	s_barrier
	s_branch .LBB0_103

.LBB0_775:
	s_or_saveexec_b64 s[44:45], s[0:1]
	s_lshl_b32 s0, s46, 2
	s_add_i32 s4, s0, s61
	s_ashr_i32 s5, s4, 31
	s_lshl_b64 s[0:1], s[4:5], 2
	s_xor_b64 exec, exec, s[44:45]
	s_cbranch_execz .LBB0_777
	v_or_b32_e32 v179, s0, v176
	v_cvt_pk_bf16_f32 v144, v216, v217
	v_cvt_pk_bf16_f32 v145, v218, v219
	v_cvt_pk_bf16_f32 v146, v152, v153
	v_mov_b64_e32 v[152:153], s[54:55]
	v_cvt_pk_bf16_f32 v147, v156, v157
	v_mad_u64_u32 v[152:153], s[6:7], v179, s25, v[152:153]
	v_mov_b32_e32 v156, 0x1600
	v_mad_i32_i24 v153, s1, v156, v153
	v_lshl_add_u64 v[152:153], v[192:193], 1, v[152:153]
	v_lshl_or_b32 v178, s4, 1, v176
	global_store_dwordx4 v[152:153], v[144:147], off sc1
	s_nop 1
	v_cvt_pk_bf16_f32 v144, v154, v155
	v_cvt_pk_bf16_f32 v145, v158, v159
	v_cvt_pk_bf16_f32 v146, v150, v151
	v_cvt_pk_bf16_f32 v147, v148, v149
	v_mov_b64_e32 v[148:149], s[56:57]
	v_mad_u64_u32 v[220:221], s[6:7], v178, s25, v[148:149]
	v_mad_i32_i24 v221, s5, v156, v221
.LBB0_777:
	s_or_b64 exec, exec, s[44:45]
	v_lshlrev_b64 v[150:151], 1, v[192:193]
	v_lshl_add_u64 v[152:153], v[220:221], 0, v[150:151]
	s_waitcnt lgkmcnt(0)
	v_pk_mul_f32 v[108:109], v[108:109], v[214:215] op_sel_hi:[1,0]
	global_store_dwordx4 v[152:153], v[144:147], off sc1
	ds_bpermute_b32 v144, v173, v108
	ds_bpermute_b32 v145, v175, v108
	v_cmp_eq_u32_e64 s[46:47], 0, v176
	s_waitcnt vmcnt(0)
	v_fma_f32 v108, v140, v108, v128
	ds_bpermute_b32 v146, v173, v109
	s_waitcnt lgkmcnt(2)
	v_cndmask_b32_e64 v158, v144, v225, s[46:47]
	s_waitcnt lgkmcnt(1)
	v_cndmask_b32_e32 v159, v145, v224, vcc
	v_fmac_f32_e32 v108, v136, v158
	ds_bpermute_b32 v147, v175, v109
	v_fmac_f32_e32 v108, v132, v159
	v_mul_f32_e32 v158, 0xbfb8aa3b, v108
	v_exp_f32_e32 v158, v158
	v_pk_mul_f32 v[110:111], v[110:111], v[214:215] op_sel_hi:[1,0]
	ds_bpermute_b32 v153, v173, v110
	s_waitcnt lgkmcnt(2)
	v_cndmask_b32_e64 v159, v146, v222, s[46:47]
	v_fma_f32 v109, v141, v109, v129
	ds_bpermute_b32 v152, v173, v111
	ds_bpermute_b32 v154, v175, v110
	s_waitcnt lgkmcnt(3)
	v_cndmask_b32_e32 v179, v147, v215, vcc
	v_fmac_f32_e32 v109, v137, v159
	ds_bpermute_b32 v155, v175, v111
	v_add_f32_e32 v158, 1.0, v158
	v_fmac_f32_e32 v109, v133, v179
	v_rcp_f32_e32 v158, v158
	v_mul_f32_e32 v159, 0xbfb8aa3b, v109
	v_exp_f32_e32 v159, v159
	s_waitcnt lgkmcnt(3)
	v_cndmask_b32_e64 v157, v153, v226, s[46:47]
	v_fma_f32 v110, v142, v110, v130
	s_waitcnt lgkmcnt(2)
	v_cndmask_b32_e64 v156, v152, v227, s[46:47]
	s_waitcnt lgkmcnt(1)
	v_cndmask_b32_e32 v179, v154, v213, vcc
	v_fmac_f32_e32 v110, v138, v157
	v_fma_f32 v111, v143, v111, v131
	v_pk_mul_f32 v[104:105], v[104:105], v[214:215] op_sel_hi:[1,0]
	s_waitcnt lgkmcnt(0)
	v_cndmask_b32_e32 v178, v155, v223, vcc
	v_mul_f32_e32 v108, v108, v158
	v_fmac_f32_e32 v110, v134, v179
	v_fmac_f32_e32 v111, v139, v156
	v_mul_f32_e32 v104, v104, v108
	v_add_f32_e32 v108, 1.0, v159
	v_mul_f32_e32 v157, 0xbfb8aa3b, v110
	v_fmac_f32_e32 v111, v135, v178
	v_rcp_f32_e32 v108, v108
	v_exp_f32_e32 v157, v157
	v_mul_f32_e32 v156, 0xbfb8aa3b, v111
	v_exp_f32_e32 v156, v156
	v_pk_mul_f32 v[102:103], v[102:103], v[214:215] op_sel_hi:[1,0]
	v_mul_f32_e32 v108, v109, v108
	v_add_f32_e32 v109, 1.0, v157
	ds_bpermute_b32 v157, v173, v103
	v_rcp_f32_e32 v109, v109
	v_add_f32_e32 v156, 1.0, v156
	ds_bpermute_b32 v158, v175, v103
	v_rcp_f32_e32 v156, v156
	v_pk_mul_f32 v[106:107], v[106:107], v[214:215] op_sel_hi:[1,0]
	v_mul_f32_e32 v105, v105, v108
	v_mul_f32_e32 v108, v110, v109
	s_waitcnt lgkmcnt(1)
	v_cndmask_b32_e64 v180, v157, v211, s[46:47]
	v_fma_f32 v103, v127, v103, v115
	v_mul_f32_e32 v106, v106, v108
	v_mul_f32_e32 v108, v111, v156
	ds_bpermute_b32 v156, v173, v102
	s_waitcnt lgkmcnt(1)
	v_cndmask_b32_e32 v181, v158, v209, vcc
	v_fmac_f32_e32 v103, v123, v180
	ds_bpermute_b32 v159, v175, v102
	v_fmac_f32_e32 v103, v119, v181
	v_mul_f32_e32 v180, 0xbfb8aa3b, v103
	v_exp_f32_e32 v180, v180
	v_pk_mul_f32 v[100:101], v[100:101], v[214:215] op_sel_hi:[1,0]
	ds_bpermute_b32 v110, v173, v101
	s_waitcnt lgkmcnt(2)
	v_cndmask_b32_e64 v181, v156, v197, s[46:47]
	v_fma_f32 v102, v126, v102, v114
	v_mul_f32_e32 v107, v107, v108
	ds_bpermute_b32 v108, v173, v100
	ds_bpermute_b32 v111, v175, v101
	s_waitcnt lgkmcnt(3)
	v_cndmask_b32_e32 v182, v159, v201, vcc
	v_fmac_f32_e32 v102, v122, v181
	ds_bpermute_b32 v109, v175, v100
	v_add_f32_e32 v180, 1.0, v180
	v_fmac_f32_e32 v102, v118, v182
	v_rcp_f32_e32 v180, v180
	v_mul_f32_e32 v181, 0xbfb8aa3b, v102
	v_exp_f32_e32 v181, v181
	s_waitcnt lgkmcnt(3)
	v_cndmask_b32_e64 v179, v110, v205, s[46:47]
	v_fma_f32 v101, v125, v101, v113
	s_waitcnt lgkmcnt(2)
	v_cndmask_b32_e64 v178, v108, v203, s[46:47]
	s_waitcnt lgkmcnt(1)
	v_cndmask_b32_e32 v182, v111, v191, vcc
	v_fmac_f32_e32 v101, v121, v179
	v_fma_f32 v100, v124, v100, v112
	v_pk_mul_f32 v[98:99], v[98:99], v[214:215] op_sel_hi:[1,0]
	s_waitcnt lgkmcnt(0)
	v_cndmask_b32_e32 v183, v109, v195, vcc
	v_mul_f32_e32 v103, v103, v180
	v_fmac_f32_e32 v101, v117, v182
	v_fmac_f32_e32 v100, v120, v178
	v_mul_f32_e32 v103, v99, v103
	v_add_f32_e32 v99, 1.0, v181
	v_mul_f32_e32 v179, 0xbfb8aa3b, v101
	v_fmac_f32_e32 v100, v116, v183
	v_rcp_f32_e32 v99, v99
	v_exp_f32_e32 v179, v179
	v_mul_f32_e32 v178, 0xbfb8aa3b, v100
	v_exp_f32_e32 v178, v178
	v_mul_f32_e32 v99, v102, v99
	v_add_f32_e32 v102, 1.0, v179
	v_rcp_f32_e32 v102, v102
	v_add_f32_e32 v178, 1.0, v178
	v_rcp_f32_e32 v178, v178
	v_pk_mul_f32 v[96:97], v[96:97], v[214:215] op_sel_hi:[1,0]
	v_mul_f32_e32 v179, v98, v99
	v_mul_f32_e32 v98, v101, v102
	v_mul_f32_e32 v97, v97, v98
	v_mul_f32_e32 v98, v100, v178
	v_mul_f32_e32 v96, v96, v98
	v_cvt_pk_bf16_f32 v98, v104, v105
	v_cvt_pk_bf16_f32 v99, v106, v107
	v_cvt_pk_bf16_f32 v100, v96, v97
	v_mov_b64_e32 v[96:97], s[52:53]
	v_cvt_pk_bf16_f32 v101, v179, v103
	v_mad_i64_i32 v[102:103], s[6:7], v204, s25, v[96:97]
	v_lshl_add_u64 v[102:103], v[102:103], 0, v[150:151]
	v_pk_mul_f32 v[92:93], v[92:93], v[212:213] op_sel_hi:[1,0]
	global_store_dwordx4 v[102:103], v[98:101], off sc1
	ds_bpermute_b32 v98, v173, v92
	ds_bpermute_b32 v99, v175, v92
	v_fma_f32 v92, v140, v92, v128
	ds_bpermute_b32 v100, v173, v93
	ds_bpermute_b32 v103, v175, v93
	s_waitcnt lgkmcnt(3)
	v_cndmask_b32_e64 v144, v98, v144, s[46:47]
	s_waitcnt lgkmcnt(2)
	v_cndmask_b32_e32 v145, v99, v145, vcc
	v_fmac_f32_e32 v92, v136, v144
	v_fmac_f32_e32 v92, v132, v145
	v_mul_f32_e32 v144, 0xbfb8aa3b, v92
	v_exp_f32_e32 v144, v144
	v_pk_mul_f32 v[94:95], v[94:95], v[212:213] op_sel_hi:[1,0]
	ds_bpermute_b32 v102, v173, v94
	s_waitcnt lgkmcnt(2)
	v_cndmask_b32_e64 v145, v100, v146, s[46:47]
	v_fma_f32 v93, v141, v93, v129
	ds_bpermute_b32 v101, v173, v95
	ds_bpermute_b32 v104, v175, v94
	s_waitcnt lgkmcnt(3)
	v_cndmask_b32_e32 v147, v103, v147, vcc
	v_fmac_f32_e32 v93, v137, v145
	ds_bpermute_b32 v105, v175, v95
	v_add_f32_e32 v144, 1.0, v144
	v_fmac_f32_e32 v93, v133, v147
	v_rcp_f32_e32 v144, v144
	v_mul_f32_e32 v145, 0xbfb8aa3b, v93
	v_exp_f32_e32 v145, v145
	s_waitcnt lgkmcnt(3)
	v_cndmask_b32_e64 v107, v102, v153, s[46:47]
	v_fma_f32 v94, v142, v94, v130
	s_waitcnt lgkmcnt(2)
	v_cndmask_b32_e64 v106, v101, v152, s[46:47]
	s_waitcnt lgkmcnt(1)
	v_cndmask_b32_e32 v147, v104, v154, vcc
	v_fmac_f32_e32 v94, v138, v107
	v_fma_f32 v95, v143, v95, v131
	v_pk_mul_f32 v[88:89], v[88:89], v[212:213] op_sel_hi:[1,0]
	s_waitcnt lgkmcnt(0)
	v_cndmask_b32_e32 v146, v105, v155, vcc
	v_mul_f32_e32 v92, v92, v144
	v_fmac_f32_e32 v94, v134, v147
	v_fmac_f32_e32 v95, v139, v106
	v_mul_f32_e32 v88, v88, v92
	v_add_f32_e32 v92, 1.0, v145
	v_mul_f32_e32 v107, 0xbfb8aa3b, v94
	v_fmac_f32_e32 v95, v135, v146
	v_rcp_f32_e32 v92, v92
	v_exp_f32_e32 v107, v107
	v_mul_f32_e32 v106, 0xbfb8aa3b, v95
	v_exp_f32_e32 v106, v106
	v_pk_mul_f32 v[86:87], v[86:87], v[212:213] op_sel_hi:[1,0]
	v_mul_f32_e32 v92, v93, v92
	v_add_f32_e32 v93, 1.0, v107
	ds_bpermute_b32 v107, v173, v87
	v_rcp_f32_e32 v93, v93
	v_add_f32_e32 v106, 1.0, v106
	ds_bpermute_b32 v144, v175, v87
	v_rcp_f32_e32 v106, v106
	v_pk_mul_f32 v[90:91], v[90:91], v[212:213] op_sel_hi:[1,0]
	v_mul_f32_e32 v89, v89, v92
	v_mul_f32_e32 v92, v94, v93
	s_waitcnt lgkmcnt(1)
	v_cndmask_b32_e64 v146, v107, v157, s[46:47]
	v_fma_f32 v87, v127, v87, v115
	v_mul_f32_e32 v90, v90, v92
	v_mul_f32_e32 v92, v95, v106
	ds_bpermute_b32 v106, v173, v86
	s_waitcnt lgkmcnt(1)
	v_cndmask_b32_e32 v147, v144, v158, vcc
	v_fmac_f32_e32 v87, v123, v146
	ds_bpermute_b32 v145, v175, v86
	v_fmac_f32_e32 v87, v119, v147
	v_mul_f32_e32 v146, 0xbfb8aa3b, v87
	v_exp_f32_e32 v146, v146
	v_pk_mul_f32 v[84:85], v[84:85], v[212:213] op_sel_hi:[1,0]
	ds_bpermute_b32 v94, v173, v85
	s_waitcnt lgkmcnt(2)
	v_cndmask_b32_e64 v147, v106, v156, s[46:47]
	v_fma_f32 v86, v126, v86, v114
	v_mul_f32_e32 v91, v91, v92
	ds_bpermute_b32 v92, v173, v84
	ds_bpermute_b32 v95, v175, v85
	s_waitcnt lgkmcnt(3)
	v_cndmask_b32_e32 v152, v145, v159, vcc
	v_fmac_f32_e32 v86, v122, v147
	ds_bpermute_b32 v93, v175, v84
	v_add_f32_e32 v146, 1.0, v146
	v_fmac_f32_e32 v86, v118, v152
	v_rcp_f32_e32 v146, v146
	v_mul_f32_e32 v147, 0xbfb8aa3b, v86
	v_exp_f32_e32 v147, v147
	s_waitcnt lgkmcnt(3)
	v_cndmask_b32_e64 v110, v94, v110, s[46:47]
	v_fma_f32 v85, v125, v85, v113
	s_waitcnt lgkmcnt(2)
	v_cndmask_b32_e64 v108, v92, v108, s[46:47]
	s_waitcnt lgkmcnt(1)
	v_cndmask_b32_e32 v111, v95, v111, vcc
	v_fmac_f32_e32 v85, v121, v110
	v_fma_f32 v84, v124, v84, v112
	v_pk_mul_f32 v[82:83], v[82:83], v[212:213] op_sel_hi:[1,0]
	s_waitcnt lgkmcnt(0)
	v_cndmask_b32_e32 v109, v93, v109, vcc
	v_mul_f32_e32 v87, v87, v146
	v_fmac_f32_e32 v85, v117, v111
	v_fmac_f32_e32 v84, v120, v108
	v_mul_f32_e32 v83, v83, v87
	v_add_f32_e32 v87, 1.0, v147
	v_mul_f32_e32 v110, 0xbfb8aa3b, v85
	v_fmac_f32_e32 v84, v116, v109
	v_rcp_f32_e32 v87, v87
	v_exp_f32_e32 v110, v110
	v_mul_f32_e32 v108, 0xbfb8aa3b, v84
	v_exp_f32_e32 v108, v108
	v_mul_f32_e32 v86, v86, v87
	v_add_f32_e32 v87, 1.0, v110
	v_rcp_f32_e32 v87, v87
	v_add_f32_e32 v108, 1.0, v108
	v_rcp_f32_e32 v108, v108
	v_pk_mul_f32 v[80:81], v[80:81], v[212:213] op_sel_hi:[1,0]
	v_mul_f32_e32 v86, v82, v86
	v_mul_f32_e32 v82, v85, v87
	v_mul_f32_e32 v82, v81, v82
	v_mul_f32_e32 v81, v84, v108
	v_mul_f32_e32 v84, v80, v81
	v_cvt_pk_bf16_f32 v80, v88, v89
	v_cvt_pk_bf16_f32 v81, v90, v91
	v_cvt_pk_bf16_f32 v82, v84, v82
	v_mad_i64_i32 v[84:85], s[6:7], v200, s25, v[96:97]
	v_lshl_add_u64 v[84:85], v[84:85], 0, v[150:151]
	v_pk_mul_f32 v[76:77], v[76:77], v[210:211] op_sel_hi:[1,0]
	v_cvt_pk_bf16_f32 v83, v86, v83
	global_store_dwordx4 v[84:85], v[80:83], off sc1
	ds_bpermute_b32 v80, v173, v76
	ds_bpermute_b32 v81, v175, v76
	v_pk_mul_f32 v[78:79], v[78:79], v[210:211] op_sel_hi:[1,0]
	v_fma_f32 v88, v140, v76, v128
	ds_bpermute_b32 v82, v173, v77
	s_waitcnt lgkmcnt(2)
	v_cndmask_b32_e64 v80, v80, v98, s[46:47]
	ds_bpermute_b32 v87, v175, v79
	s_waitcnt lgkmcnt(2)
	v_cndmask_b32_e32 v81, v81, v99, vcc
	v_fmac_f32_e32 v88, v136, v80
	ds_bpermute_b32 v85, v175, v77
	v_fmac_f32_e32 v88, v132, v81
	v_mul_f32_e32 v80, 0xbfb8aa3b, v88
	v_exp_f32_e32 v80, v80
	s_waitcnt lgkmcnt(2)
	v_cndmask_b32_e64 v81, v82, v100, s[46:47]
	s_waitcnt lgkmcnt(1)
	v_cndmask_b32_e32 v82, v87, v105, vcc
	v_fma_f32 v87, v141, v77, v129
	s_waitcnt lgkmcnt(0)
	v_cndmask_b32_e32 v85, v85, v103, vcc
	v_fmac_f32_e32 v87, v137, v81
	v_add_f32_e32 v80, 1.0, v80
	v_fmac_f32_e32 v87, v133, v85
	ds_bpermute_b32 v84, v173, v78
	v_rcp_f32_e32 v80, v80
	v_mul_f32_e32 v81, 0xbfb8aa3b, v87
	ds_bpermute_b32 v86, v175, v78
	v_exp_f32_e32 v81, v81
	ds_bpermute_b32 v83, v173, v79
	v_pk_mul_f32 v[72:73], v[72:73], v[210:211] op_sel_hi:[1,0]
	v_mul_f32_e32 v80, v88, v80
	s_waitcnt lgkmcnt(2)
	v_cndmask_b32_e64 v84, v84, v102, s[46:47]
	v_mul_f32_e32 v72, v72, v80
	v_add_f32_e32 v80, 1.0, v81
	v_fma_f32 v81, v142, v78, v130
	s_waitcnt lgkmcnt(1)
	v_cndmask_b32_e32 v85, v86, v104, vcc
	v_fmac_f32_e32 v81, v138, v84
	s_waitcnt lgkmcnt(0)
	v_cndmask_b32_e64 v83, v83, v101, s[46:47]
	v_fmac_f32_e32 v81, v134, v85
	v_fma_f32 v85, v143, v79, v131
	v_fmac_f32_e32 v85, v139, v83
	v_mul_f32_e32 v84, 0xbfb8aa3b, v81
	v_fmac_f32_e32 v85, v135, v82
	v_exp_f32_e32 v84, v84
	v_mul_f32_e32 v82, 0xbfb8aa3b, v85
	v_exp_f32_e32 v82, v82
	v_rcp_f32_e32 v80, v80
	v_add_f32_e32 v83, 1.0, v84
	v_rcp_f32_e32 v83, v83
	v_add_f32_e32 v82, 1.0, v82
	v_rcp_f32_e32 v82, v82
	v_mul_f32_e32 v80, v87, v80
	v_pk_mul_f32 v[74:75], v[74:75], v[210:211] op_sel_hi:[1,0]
	v_mul_f32_e32 v73, v73, v80
	v_mul_f32_e32 v80, v81, v83
	v_pk_mul_f32 v[70:71], v[70:71], v[210:211] op_sel_hi:[1,0]
	v_mul_f32_e32 v74, v74, v80
	v_mul_f32_e32 v80, v85, v82
	ds_bpermute_b32 v85, v173, v71
	ds_bpermute_b32 v86, v175, v71
	v_fma_f32 v88, v127, v71, v115
	v_pk_mul_f32 v[68:69], v[68:69], v[210:211] op_sel_hi:[1,0]
	ds_bpermute_b32 v82, v173, v69
	s_waitcnt lgkmcnt(2)
	v_cndmask_b32_e64 v85, v85, v107, s[46:47]
	s_waitcnt lgkmcnt(1)
	v_cndmask_b32_e32 v86, v86, v144, vcc
	v_fmac_f32_e32 v88, v123, v85
	v_fmac_f32_e32 v88, v119, v86
	v_mul_f32_e32 v85, 0xbfb8aa3b, v88
	v_exp_f32_e32 v85, v85
	ds_bpermute_b32 v84, v173, v70
	ds_bpermute_b32 v87, v175, v70
	ds_bpermute_b32 v83, v175, v69
	v_add_f32_e32 v85, 1.0, v85
	v_rcp_f32_e32 v85, v85
	v_mul_f32_e32 v75, v75, v80
	ds_bpermute_b32 v80, v173, v68
	ds_bpermute_b32 v81, v175, v68
	v_pk_mul_f32 v[66:67], v[66:67], v[210:211] op_sel_hi:[1,0]
	v_mul_f32_e32 v85, v88, v85
	s_waitcnt lgkmcnt(5)
	v_cndmask_b32_e64 v82, v82, v94, s[46:47]
	s_waitcnt lgkmcnt(4)
	v_cndmask_b32_e64 v84, v84, v106, s[46:47]
	s_waitcnt lgkmcnt(3)
	v_cndmask_b32_e32 v86, v87, v145, vcc
	v_fma_f32 v87, v126, v70, v114
	v_mul_f32_e32 v67, v67, v85
	v_fma_f32 v85, v125, v69, v113
	v_fmac_f32_e32 v87, v122, v84
	s_waitcnt lgkmcnt(2)
	v_cndmask_b32_e32 v83, v83, v95, vcc
	v_fmac_f32_e32 v85, v121, v82
	s_waitcnt lgkmcnt(1)
	v_cndmask_b32_e64 v80, v80, v92, s[46:47]
	v_fmac_f32_e32 v87, v118, v86
	v_fmac_f32_e32 v85, v117, v83
	v_fma_f32 v83, v124, v68, v112
	s_waitcnt lgkmcnt(0)
	v_cndmask_b32_e32 v81, v81, v93, vcc
	v_mul_f32_e32 v84, 0xbfb8aa3b, v87
	v_fmac_f32_e32 v83, v120, v80
	v_exp_f32_e32 v84, v84
	v_mul_f32_e32 v82, 0xbfb8aa3b, v85
	v_fmac_f32_e32 v83, v116, v81
	v_exp_f32_e32 v82, v82
	v_mul_f32_e32 v80, 0xbfb8aa3b, v83
	v_exp_f32_e32 v80, v80
	v_add_f32_e32 v84, 1.0, v84
	v_rcp_f32_e32 v84, v84
	v_add_f32_e32 v82, 1.0, v82
	v_rcp_f32_e32 v82, v82
	v_add_f32_e32 v80, 1.0, v80
	v_rcp_f32_e32 v80, v80
	v_mul_f32_e32 v81, v87, v84
	v_pk_mul_f32 v[64:65], v[64:65], v[210:211] op_sel_hi:[1,0]
	v_mul_f32_e32 v81, v66, v81
	v_mul_f32_e32 v66, v85, v82
	v_mul_f32_e32 v66, v65, v66
	v_mul_f32_e32 v65, v83, v80
	v_mul_f32_e32 v80, v64, v65
	v_cvt_pk_bf16_f32 v64, v72, v73
	v_mad_i64_i32 v[72:73], s[6:7], v196, s25, v[96:97]
	v_cmp_lt_u32_e64 s[44:45], 13, v176
	v_lshl_add_u64 v[148:149], v[176:177], 0, -12
	v_lshl_add_u64 v[72:73], v[72:73], 0, v[150:151]
	v_cvt_pk_bf16_f32 v65, v74, v75
	v_cvt_pk_bf16_f32 v66, v80, v66
	v_cvt_pk_bf16_f32 v67, v81, v67
	global_store_dwordx4 v[72:73], v[64:67], off sc1
	s_and_saveexec_b64 s[6:7], s[44:45]
	s_cbranch_execz .LBB0_779
	v_lshl_add_u64 v[72:73], v[148:149], 0, s[0:1]
	v_cvt_pk_bf16_f32 v64, v76, v77
	v_cvt_pk_bf16_f32 v65, v78, v79
	v_cvt_pk_bf16_f32 v66, v68, v69
	v_mov_b64_e32 v[68:69], s[54:55]
	v_mad_u64_u32 v[68:69], s[0:1], v72, s25, v[68:69]
	v_mad_i32_i24 v69, v73, s25, v69
	v_lshl_add_u64 v[68:69], v[192:193], 1, v[68:69]
	v_cvt_pk_bf16_f32 v67, v70, v71
	global_store_dwordx4 v[68:69], v[64:67], off sc1

.LBB0_781:
	s_or_saveexec_b64 s[48:49], s[0:1]
	s_add_i32 s4, s4, 2
	s_ashr_i32 s5, s4, 31
	s_lshl_b64 s[0:1], s[4:5], 2
	s_xor_b64 exec, exec, s[48:49]
	s_cbranch_execz .LBB0_783
	v_or_b32_e32 v69, s0, v176
	v_cvt_pk_bf16_f32 v48, v64, v65
	v_cvt_pk_bf16_f32 v49, v66, v67
	v_cvt_pk_bf16_f32 v50, v56, v57
	v_mov_b64_e32 v[56:57], s[54:55]
	v_cvt_pk_bf16_f32 v51, v58, v59
	v_mad_u64_u32 v[56:57], s[6:7], v69, s25, v[56:57]
	v_mov_b32_e32 v58, 0x1600
	v_mad_i32_i24 v57, s1, v58, v57
	v_lshl_add_u64 v[56:57], v[192:193], 1, v[56:57]
	v_lshl_or_b32 v68, s4, 1, v176
	global_store_dwordx4 v[56:57], v[48:51], off sc1
	s_nop 1
	v_cvt_pk_bf16_f32 v48, v60, v61
	v_cvt_pk_bf16_f32 v49, v62, v63
	v_cvt_pk_bf16_f32 v50, v54, v55
	v_cvt_pk_bf16_f32 v51, v52, v53
	v_mov_b64_e32 v[52:53], s[56:57]
	v_mad_u64_u32 v[68:69], s[6:7], v68, s25, v[52:53]
	v_mad_i32_i24 v69, s5, v58, v69
.LBB0_783:
	s_or_b64 exec, exec, s[48:49]
	v_lshl_add_u64 v[52:53], v[68:69], 0, v[150:151]
	v_pk_mul_f32 v[44:45], v[44:45], v[206:207] op_sel_hi:[1,0]
	global_store_dwordx4 v[52:53], v[48:51], off sc1
	ds_bpermute_b32 v48, v173, v44
	ds_bpermute_b32 v49, v175, v44
	v_fma_f32 v44, v140, v44, v128
	ds_bpermute_b32 v50, v173, v45
	ds_bpermute_b32 v53, v175, v45
	s_waitcnt lgkmcnt(3)
	v_cndmask_b32_e64 v58, v48, v83, s[46:47]
	s_waitcnt lgkmcnt(2)
	v_cndmask_b32_e32 v59, v49, v82, vcc
	v_fmac_f32_e32 v44, v136, v58
	v_fmac_f32_e32 v44, v132, v59
	v_mul_f32_e32 v58, 0xbfb8aa3b, v44
	v_exp_f32_e32 v58, v58
	v_pk_mul_f32 v[46:47], v[46:47], v[206:207] op_sel_hi:[1,0]
	ds_bpermute_b32 v52, v173, v46
	s_waitcnt lgkmcnt(2)
	v_cndmask_b32_e64 v59, v50, v80, s[46:47]
	v_fma_f32 v45, v141, v45, v129
	ds_bpermute_b32 v51, v173, v47
	ds_bpermute_b32 v54, v175, v46
	s_waitcnt lgkmcnt(3)
	v_cndmask_b32_e32 v61, v53, v79, vcc
	v_fmac_f32_e32 v45, v137, v59
	ds_bpermute_b32 v55, v175, v47
	v_add_f32_e32 v58, 1.0, v58
	v_fmac_f32_e32 v45, v133, v61
	v_rcp_f32_e32 v58, v58
	v_mul_f32_e32 v59, 0xbfb8aa3b, v45
	v_exp_f32_e32 v59, v59
	s_waitcnt lgkmcnt(3)
	v_cndmask_b32_e64 v57, v52, v84, s[46:47]
	v_fma_f32 v46, v142, v46, v130
	s_waitcnt lgkmcnt(2)
	v_cndmask_b32_e64 v56, v51, v85, s[46:47]
	s_waitcnt lgkmcnt(1)
	v_cndmask_b32_e32 v61, v54, v78, vcc
	v_fmac_f32_e32 v46, v138, v57
	v_fma_f32 v47, v143, v47, v131
	v_pk_mul_f32 v[40:41], v[40:41], v[206:207] op_sel_hi:[1,0]
	s_waitcnt lgkmcnt(0)
	v_cndmask_b32_e32 v60, v55, v81, vcc
	v_mul_f32_e32 v44, v44, v58
	v_fmac_f32_e32 v46, v134, v61
	v_fmac_f32_e32 v47, v139, v56
	v_mul_f32_e32 v40, v40, v44
	v_add_f32_e32 v44, 1.0, v59
	v_mul_f32_e32 v57, 0xbfb8aa3b, v46
	v_fmac_f32_e32 v47, v135, v60
	v_rcp_f32_e32 v44, v44
	v_exp_f32_e32 v57, v57
	v_mul_f32_e32 v56, 0xbfb8aa3b, v47
	v_exp_f32_e32 v56, v56
	v_mul_f32_e32 v44, v45, v44
	v_add_f32_e32 v45, 1.0, v57
	v_rcp_f32_e32 v45, v45
	v_add_f32_e32 v56, 1.0, v56
	v_rcp_f32_e32 v56, v56
	v_pk_mul_f32 v[42:43], v[42:43], v[206:207] op_sel_hi:[1,0]
	v_mul_f32_e32 v41, v41, v44
	v_mul_f32_e32 v44, v46, v45
	v_pk_mul_f32 v[38:39], v[38:39], v[206:207] op_sel_hi:[1,0]
	v_mul_f32_e32 v42, v42, v44
	v_mul_f32_e32 v44, v47, v56
	ds_bpermute_b32 v56, v173, v39
	ds_bpermute_b32 v58, v175, v39
	v_fma_f32 v39, v127, v39, v115
	ds_bpermute_b32 v47, v173, v38
	ds_bpermute_b32 v59, v175, v38
	s_waitcnt lgkmcnt(3)
	v_cndmask_b32_e64 v61, v56, v77, s[46:47]
	s_waitcnt lgkmcnt(2)
	v_cndmask_b32_e32 v63, v58, v75, vcc
	v_fmac_f32_e32 v39, v123, v61
	v_fmac_f32_e32 v39, v119, v63
	v_mul_f32_e32 v61, 0xbfb8aa3b, v39
	v_exp_f32_e32 v61, v61
	v_pk_mul_f32 v[36:37], v[36:37], v[206:207] op_sel_hi:[1,0]
	ds_bpermute_b32 v46, v173, v37
	s_waitcnt lgkmcnt(2)
	v_cndmask_b32_e64 v60, v47, v76, s[46:47]
	v_fma_f32 v38, v126, v38, v114
	v_mul_f32_e32 v43, v43, v44
	ds_bpermute_b32 v44, v173, v36
	ds_bpermute_b32 v57, v175, v37
	s_waitcnt lgkmcnt(3)
	v_cndmask_b32_e32 v64, v59, v73, vcc
	v_fmac_f32_e32 v38, v122, v60
	ds_bpermute_b32 v45, v175, v36
	v_add_f32_e32 v61, 1.0, v61
	v_fmac_f32_e32 v38, v118, v64
	v_rcp_f32_e32 v61, v61
	v_mul_f32_e32 v60, 0xbfb8aa3b, v38
	v_exp_f32_e32 v60, v60
	s_waitcnt lgkmcnt(3)
	v_cndmask_b32_e64 v63, v46, v72, s[46:47]
	v_fma_f32 v37, v125, v37, v113
	s_waitcnt lgkmcnt(2)
	v_cndmask_b32_e64 v62, v44, v74, s[46:47]
	s_waitcnt lgkmcnt(1)
	v_cndmask_b32_e32 v64, v57, v70, vcc
	v_fmac_f32_e32 v37, v121, v63
	v_fma_f32 v36, v124, v36, v112
	v_pk_mul_f32 v[34:35], v[34:35], v[206:207] op_sel_hi:[1,0]
	s_waitcnt lgkmcnt(0)
	v_cndmask_b32_e32 v65, v45, v71, vcc
	v_mul_f32_e32 v39, v39, v61
	v_fmac_f32_e32 v37, v117, v64
	v_fmac_f32_e32 v36, v120, v62
	v_mul_f32_e32 v39, v35, v39
	v_add_f32_e32 v35, 1.0, v60
	v_mul_f32_e32 v60, 0xbfb8aa3b, v37
	v_fmac_f32_e32 v36, v116, v65
	v_rcp_f32_e32 v35, v35
	v_exp_f32_e32 v60, v60
	v_mul_f32_e32 v61, 0xbfb8aa3b, v36
	v_exp_f32_e32 v61, v61
	v_mul_f32_e32 v35, v38, v35
	v_add_f32_e32 v38, 1.0, v60
	v_rcp_f32_e32 v38, v38
	v_add_f32_e32 v60, 1.0, v61
	v_rcp_f32_e32 v60, v60
	v_pk_mul_f32 v[32:33], v[32:33], v[206:207] op_sel_hi:[1,0]
	v_mul_f32_e32 v61, v34, v35
	v_mul_f32_e32 v34, v37, v38
	v_mul_f32_e32 v33, v33, v34
	v_mul_f32_e32 v34, v36, v60
	v_mul_f32_e32 v32, v32, v34
	v_cvt_pk_bf16_f32 v34, v40, v41
	v_cvt_pk_bf16_f32 v35, v42, v43
	v_cvt_pk_bf16_f32 v36, v32, v33
	v_mov_b64_e32 v[32:33], s[52:53]
	v_cvt_pk_bf16_f32 v37, v61, v39
	v_mad_i64_i32 v[38:39], s[4:5], v190, s25, v[32:33]
	v_lshl_add_u64 v[38:39], v[38:39], 0, v[150:151]
	v_pk_mul_f32 v[28:29], v[28:29], v[202:203] op_sel_hi:[1,0]
	global_store_dwordx4 v[38:39], v[34:37], off sc1
	ds_bpermute_b32 v34, v173, v28
	ds_bpermute_b32 v35, v175, v28
	v_fma_f32 v28, v140, v28, v128
	v_pk_mul_f32 v[30:31], v[30:31], v[202:203] op_sel_hi:[1,0]
	ds_bpermute_b32 v36, v173, v29
	s_waitcnt lgkmcnt(2)
	v_cndmask_b32_e64 v48, v34, v48, s[46:47]
	s_waitcnt lgkmcnt(1)
	v_cndmask_b32_e32 v49, v35, v49, vcc
	v_fmac_f32_e32 v28, v136, v48
	ds_bpermute_b32 v37, v173, v31
	ds_bpermute_b32 v39, v175, v29
	v_fmac_f32_e32 v28, v132, v49
	v_mul_f32_e32 v48, 0xbfb8aa3b, v28
	v_exp_f32_e32 v48, v48
	ds_bpermute_b32 v38, v173, v30
	s_waitcnt lgkmcnt(3)
	v_cndmask_b32_e64 v49, v36, v50, s[46:47]
	v_fma_f32 v29, v141, v29, v129
	ds_bpermute_b32 v40, v175, v30
	s_waitcnt lgkmcnt(3)
	v_cndmask_b32_e64 v42, v37, v51, s[46:47]
	s_waitcnt lgkmcnt(2)
	v_cndmask_b32_e32 v51, v39, v53, vcc
	v_fmac_f32_e32 v29, v137, v49
	ds_bpermute_b32 v41, v175, v31
	v_add_f32_e32 v48, 1.0, v48
	v_fmac_f32_e32 v29, v133, v51
	v_rcp_f32_e32 v48, v48
	v_mul_f32_e32 v49, 0xbfb8aa3b, v29
	v_exp_f32_e32 v49, v49
	s_waitcnt lgkmcnt(2)
	v_cndmask_b32_e64 v43, v38, v52, s[46:47]
	v_fma_f32 v30, v142, v30, v130
	s_waitcnt lgkmcnt(1)
	v_cndmask_b32_e32 v51, v40, v54, vcc
	v_fmac_f32_e32 v30, v138, v43
	v_fma_f32 v31, v143, v31, v131
	v_pk_mul_f32 v[24:25], v[24:25], v[202:203] op_sel_hi:[1,0]
	s_waitcnt lgkmcnt(0)
	v_cndmask_b32_e32 v50, v41, v55, vcc
	v_mul_f32_e32 v28, v28, v48
	v_fmac_f32_e32 v30, v134, v51
	v_fmac_f32_e32 v31, v139, v42
	v_mul_f32_e32 v24, v24, v28
	v_add_f32_e32 v28, 1.0, v49
	v_mul_f32_e32 v43, 0xbfb8aa3b, v30
	v_fmac_f32_e32 v31, v135, v50
	v_rcp_f32_e32 v28, v28
	v_exp_f32_e32 v43, v43
	v_mul_f32_e32 v42, 0xbfb8aa3b, v31
	v_exp_f32_e32 v42, v42
	v_mul_f32_e32 v28, v29, v28
	v_add_f32_e32 v29, 1.0, v43
	v_rcp_f32_e32 v29, v29
	v_add_f32_e32 v42, 1.0, v42
	v_rcp_f32_e32 v42, v42
	v_pk_mul_f32 v[26:27], v[26:27], v[202:203] op_sel_hi:[1,0]
	v_mul_f32_e32 v25, v25, v28
	v_mul_f32_e32 v28, v30, v29
	v_pk_mul_f32 v[22:23], v[22:23], v[202:203] op_sel_hi:[1,0]
	v_mul_f32_e32 v26, v26, v28
	v_mul_f32_e32 v28, v31, v42
	ds_bpermute_b32 v42, v173, v23
	ds_bpermute_b32 v48, v175, v23
	v_fma_f32 v23, v127, v23, v115
	ds_bpermute_b32 v31, v173, v22
	ds_bpermute_b32 v49, v175, v22
	s_waitcnt lgkmcnt(3)
	v_cndmask_b32_e64 v50, v42, v56, s[46:47]
	s_waitcnt lgkmcnt(2)
	v_cndmask_b32_e32 v51, v48, v58, vcc
	v_fmac_f32_e32 v23, v123, v50
	v_fmac_f32_e32 v23, v119, v51
	v_mul_f32_e32 v50, 0xbfb8aa3b, v23
	v_exp_f32_e32 v50, v50
	v_pk_mul_f32 v[20:21], v[20:21], v[202:203] op_sel_hi:[1,0]
	ds_bpermute_b32 v30, v173, v21
	s_waitcnt lgkmcnt(2)
	v_cndmask_b32_e64 v47, v31, v47, s[46:47]
	v_fma_f32 v22, v126, v22, v114
	v_mul_f32_e32 v27, v27, v28
	ds_bpermute_b32 v28, v173, v20
	ds_bpermute_b32 v43, v175, v21
	s_waitcnt lgkmcnt(3)
	v_cndmask_b32_e32 v51, v49, v59, vcc
	v_fmac_f32_e32 v22, v122, v47
	ds_bpermute_b32 v29, v175, v20
	v_add_f32_e32 v50, 1.0, v50
	v_fmac_f32_e32 v22, v118, v51
	v_rcp_f32_e32 v50, v50
	v_mul_f32_e32 v47, 0xbfb8aa3b, v22
	v_exp_f32_e32 v47, v47
	s_waitcnt lgkmcnt(3)
	v_cndmask_b32_e64 v46, v30, v46, s[46:47]
	v_fma_f32 v21, v125, v21, v113
	s_waitcnt lgkmcnt(2)
	v_cndmask_b32_e64 v44, v28, v44, s[46:47]
	s_waitcnt lgkmcnt(1)
	v_cndmask_b32_e32 v51, v43, v57, vcc
	v_fmac_f32_e32 v21, v121, v46
	v_fma_f32 v20, v124, v20, v112
	v_pk_mul_f32 v[18:19], v[18:19], v[202:203] op_sel_hi:[1,0]
	s_waitcnt lgkmcnt(0)
	v_cndmask_b32_e32 v45, v29, v45, vcc
	v_mul_f32_e32 v23, v23, v50
	v_fmac_f32_e32 v21, v117, v51
	v_fmac_f32_e32 v20, v120, v44
	v_mul_f32_e32 v19, v19, v23
	v_add_f32_e32 v23, 1.0, v47
	v_mul_f32_e32 v46, 0xbfb8aa3b, v21
	v_fmac_f32_e32 v20, v116, v45
	v_rcp_f32_e32 v23, v23
	v_exp_f32_e32 v46, v46
	v_mul_f32_e32 v44, 0xbfb8aa3b, v20
	v_exp_f32_e32 v44, v44
	v_mul_f32_e32 v22, v22, v23
	v_add_f32_e32 v23, 1.0, v46
	v_rcp_f32_e32 v23, v23
	v_add_f32_e32 v44, 1.0, v44
	v_rcp_f32_e32 v44, v44
	v_pk_mul_f32 v[16:17], v[16:17], v[202:203] op_sel_hi:[1,0]
	v_mul_f32_e32 v22, v18, v22
	v_mul_f32_e32 v18, v21, v23
	v_mul_f32_e32 v18, v17, v18
	v_mul_f32_e32 v17, v20, v44
	v_mul_f32_e32 v20, v16, v17
	v_cvt_pk_bf16_f32 v16, v24, v25
	v_cvt_pk_bf16_f32 v17, v26, v27
	v_cvt_pk_bf16_f32 v18, v20, v18
	v_mad_i64_i32 v[20:21], s[4:5], v174, s25, v[32:33]
	v_lshl_add_u64 v[20:21], v[20:21], 0, v[150:151]
	v_pk_mul_f32 v[12:13], v[12:13], v[198:199] op_sel_hi:[1,0]
	v_cvt_pk_bf16_f32 v19, v22, v19
	global_store_dwordx4 v[20:21], v[16:19], off sc1
	ds_bpermute_b32 v16, v173, v12
	ds_bpermute_b32 v17, v175, v12
	v_pk_mul_f32 v[14:15], v[14:15], v[198:199] op_sel_hi:[1,0]
	v_fma_f32 v24, v140, v12, v128
	ds_bpermute_b32 v18, v173, v13
	s_waitcnt lgkmcnt(2)
	v_cndmask_b32_e64 v16, v16, v34, s[46:47]
	ds_bpermute_b32 v23, v175, v15
	s_waitcnt lgkmcnt(2)
	v_cndmask_b32_e32 v17, v17, v35, vcc
	v_fmac_f32_e32 v24, v136, v16
	ds_bpermute_b32 v21, v175, v13
	v_fmac_f32_e32 v24, v132, v17
	v_mul_f32_e32 v16, 0xbfb8aa3b, v24
	v_exp_f32_e32 v16, v16
	s_waitcnt lgkmcnt(2)
	v_cndmask_b32_e64 v17, v18, v36, s[46:47]
	s_waitcnt lgkmcnt(1)
	v_cndmask_b32_e32 v18, v23, v41, vcc
	v_fma_f32 v23, v141, v13, v129
	s_waitcnt lgkmcnt(0)
	v_cndmask_b32_e32 v21, v21, v39, vcc
	v_fmac_f32_e32 v23, v137, v17
	v_add_f32_e32 v16, 1.0, v16
	v_fmac_f32_e32 v23, v133, v21
	ds_bpermute_b32 v20, v173, v14
	v_rcp_f32_e32 v16, v16
	v_mul_f32_e32 v17, 0xbfb8aa3b, v23
	ds_bpermute_b32 v22, v175, v14
	v_exp_f32_e32 v17, v17
	v_pk_mul_f32 v[8:9], v[8:9], v[198:199] op_sel_hi:[1,0]
	v_mul_f32_e32 v16, v24, v16
	s_waitcnt lgkmcnt(1)
	v_cndmask_b32_e64 v20, v20, v38, s[46:47]
	v_mul_f32_e32 v8, v8, v16
	v_add_f32_e32 v16, 1.0, v17
	v_fma_f32 v17, v142, v14, v130
	s_waitcnt lgkmcnt(0)
	v_cndmask_b32_e32 v21, v22, v40, vcc
	v_fmac_f32_e32 v17, v138, v20
	ds_bpermute_b32 v19, v173, v15
	v_fmac_f32_e32 v17, v134, v21
	v_mul_f32_e32 v20, 0xbfb8aa3b, v17
	v_exp_f32_e32 v20, v20
	v_fmac_f32_e32 v131, v143, v15
	s_waitcnt lgkmcnt(0)
	v_cndmask_b32_e64 v19, v19, v37, s[46:47]
	v_pk_mul_f32 v[6:7], v[6:7], v[198:199] op_sel_hi:[1,0]
	v_fmac_f32_e32 v131, v139, v19
	v_add_f32_e32 v19, 1.0, v20
	ds_bpermute_b32 v20, v173, v7
	ds_bpermute_b32 v22, v175, v7
	v_fmac_f32_e32 v131, v135, v18
	v_mul_f32_e32 v18, 0xbfb8aa3b, v131
	v_exp_f32_e32 v18, v18
	s_waitcnt lgkmcnt(1)
	v_cndmask_b32_e64 v20, v20, v42, s[46:47]
	v_fma_f32 v24, v127, v7, v115
	s_waitcnt lgkmcnt(0)
	v_cndmask_b32_e32 v22, v22, v48, vcc
	v_fmac_f32_e32 v24, v123, v20
	v_fmac_f32_e32 v24, v119, v22
	v_rcp_f32_e32 v16, v16
	v_mul_f32_e32 v20, 0xbfb8aa3b, v24
	v_rcp_f32_e32 v19, v19
	v_add_f32_e32 v18, 1.0, v18
	v_exp_f32_e32 v20, v20
	v_rcp_f32_e32 v18, v18
	v_mul_f32_e32 v16, v23, v16
	v_pk_mul_f32 v[10:11], v[10:11], v[198:199] op_sel_hi:[1,0]
	v_mul_f32_e32 v9, v9, v16
	v_mul_f32_e32 v16, v17, v19
	v_pk_mul_f32 v[4:5], v[4:5], v[198:199] op_sel_hi:[1,0]
	ds_bpermute_b32 v19, v173, v6
	ds_bpermute_b32 v23, v175, v6
	v_add_f32_e32 v20, 1.0, v20
	v_mul_f32_e32 v10, v10, v16
	v_mul_f32_e32 v16, v131, v18
	ds_bpermute_b32 v18, v173, v5
	v_rcp_f32_e32 v20, v20
	v_mul_f32_e32 v11, v11, v16
	ds_bpermute_b32 v16, v173, v4
	ds_bpermute_b32 v21, v175, v5
	ds_bpermute_b32 v17, v175, v4
	v_pk_mul_f32 v[2:3], v[2:3], v[198:199] op_sel_hi:[1,0]
	s_waitcnt lgkmcnt(5)
	v_cndmask_b32_e64 v19, v19, v31, s[46:47]
	s_waitcnt lgkmcnt(4)
	v_cndmask_b32_e32 v22, v23, v49, vcc
	v_fma_f32 v23, v126, v6, v114
	v_mul_f32_e32 v20, v24, v20
	s_waitcnt lgkmcnt(3)
	v_cndmask_b32_e64 v18, v18, v30, s[46:47]
	v_fmac_f32_e32 v23, v122, v19
	v_mul_f32_e32 v3, v3, v20
	v_fma_f32 v20, v125, v5, v113
	s_waitcnt lgkmcnt(2)
	v_cndmask_b32_e64 v16, v16, v28, s[46:47]
	v_fmac_f32_e32 v23, v118, v22
	s_waitcnt lgkmcnt(1)
	v_cndmask_b32_e32 v21, v21, v43, vcc
	v_fmac_f32_e32 v20, v121, v18
	v_fmac_f32_e32 v112, v124, v4
	s_waitcnt lgkmcnt(0)
	v_cndmask_b32_e32 v17, v17, v29, vcc
	v_mul_f32_e32 v19, 0xbfb8aa3b, v23
	v_fmac_f32_e32 v20, v117, v21
	v_fmac_f32_e32 v112, v120, v16
	v_exp_f32_e32 v19, v19
	v_mul_f32_e32 v18, 0xbfb8aa3b, v20
	v_fmac_f32_e32 v112, v116, v17
	v_exp_f32_e32 v18, v18
	v_mul_f32_e32 v16, 0xbfb8aa3b, v112
	v_exp_f32_e32 v16, v16
	v_add_f32_e32 v19, 1.0, v19
	v_rcp_f32_e32 v19, v19
	v_add_f32_e32 v18, 1.0, v18
	v_rcp_f32_e32 v18, v18
	v_add_f32_e32 v16, 1.0, v16
	v_rcp_f32_e32 v16, v16
	v_mul_f32_e32 v17, v23, v19
	v_pk_mul_f32 v[0:1], v[0:1], v[198:199] op_sel_hi:[1,0]
	v_mul_f32_e32 v17, v2, v17
	v_mul_f32_e32 v2, v20, v18
	v_mul_f32_e32 v2, v1, v2
	v_mul_f32_e32 v1, v112, v16
	v_mul_f32_e32 v16, v0, v1
	v_cvt_pk_bf16_f32 v0, v8, v9
	v_mad_i64_i32 v[8:9], s[4:5], v172, s25, v[32:33]
	v_lshl_add_u64 v[8:9], v[8:9], 0, v[150:151]
	v_cvt_pk_bf16_f32 v1, v10, v11
	v_cvt_pk_bf16_f32 v2, v16, v2
	v_cvt_pk_bf16_f32 v3, v17, v3
	global_store_dwordx4 v[8:9], v[0:3], off sc1
	s_and_saveexec_b64 s[4:5], s[44:45]
	s_cbranch_execz .LBB0_785
	v_lshl_add_u64 v[8:9], v[148:149], 0, s[0:1]
	v_cvt_pk_bf16_f32 v0, v12, v13
	v_cvt_pk_bf16_f32 v1, v14, v15
	v_cvt_pk_bf16_f32 v2, v4, v5
	v_mov_b64_e32 v[4:5], s[54:55]
	v_mad_u64_u32 v[4:5], s[0:1], v8, s25, v[4:5]
	v_mad_i32_i24 v5, v9, s25, v5
	v_lshl_add_u64 v[4:5], v[192:193], 1, v[4:5]
	v_cvt_pk_bf16_f32 v3, v6, v7
	global_store_dwordx4 v[4:5], v[0:3], off sc1
